# bundle plus context attention spread over all workgroups on waves 0-3 (one task per SIMD)
# speedup vs baseline: 1.0074x; 1.0074x over previous
.LBB0_328:
	s_lshl_b32 s0, s92, 2
	s_add_i32 s0, s0, s12
	s_cmp_lt_u32 s12, 4
	s_cselect_b32 s35, s0, 0x7fff
	s_cmpk_gt_i32 s35, 0x3ff
	v_readlane_b32 s2, v250, 23
	s_cselect_b64 s[0:1], -1, 0
	v_readlane_b32 s3, v250, 24
	s_or_b64 s[0:1], s[2:3], s[0:1]
	v_readlane_b32 s14, v252, 51
	s_and_b64 vcc, exec, s[0:1]
	v_readlane_b32 s2, v252, 28
	v_readlane_b32 s3, v252, 29
	v_readlane_b32 s15, v252, 52
	s_mov_b32 s13, 0x20000
	s_cbranch_vccnz .LBB0_331
	v_readlane_b32 s0, v252, 55
	v_mov_b32_e32 v173, v195
	v_readlane_b32 s1, v252, 56
	v_cmp_lt_i32_e32 vcc, v236, v234
	v_readlane_b32 s52, v252, 12
	v_lshl_add_u64 v[148:149], s[0:1], 0, v[172:173]
	s_lshl_b32 s0, s12, 3
	v_readlane_b32 s1, v251, 56
	v_cndmask_b32_e32 v2, v233, v236, vcc
	v_cmp_lt_i32_e32 vcc, v235, v234
	s_lshl_b32 s4, s35, 3
	s_lshl_b32 s0, s12, 4
	v_readlane_b32 s1, v251, 63
	v_lshlrev_b32_e32 v176, 2, v2
	v_cndmask_b32_e32 v2, v233, v235, vcc
	v_mov_b32_e32 v175, v195
	v_readlane_b32 s60, v252, 20
	v_readlane_b32 s61, v252, 21
	s_lshl_b32 s5, s35, 4
	s_lshl_b32 s0, s12, 1
	v_readlane_b32 s1, v250, 0
	v_lshlrev_b32_e32 v177, 2, v2
	s_mov_b64 s[22:23], 0x3000
	s_mov_b64 s[20:21], 0x2000
	v_lshl_add_u64 v[146:147], s[60:61], 0, v[174:175]
	s_lshl_b32 s6, s35, 1
	v_lshlrev_b32_e32 v194, 1, v170
	v_readlane_b32 s9, v250, 17
	v_readlane_b32 s12, v250, 1
	s_mov_b32 s17, 0x240000
	v_readlane_b32 s53, v252, 13
	v_readlane_b32 s54, v252, 14
	v_readlane_b32 s55, v252, 15
	v_readlane_b32 s56, v252, 16
	v_readlane_b32 s57, v252, 17
	v_readlane_b32 s58, v252, 18
	v_readlane_b32 s59, v252, 19
	v_readlane_b32 s62, v252, 22
	v_readlane_b32 s63, v252, 23
	v_readlane_b32 s64, v252, 24
	v_readlane_b32 s65, v252, 25
	v_readlane_b32 s66, v252, 26
	v_readlane_b32 s67, v252, 27
